# phase 8 transpose: next tile's loads issued once the current tile is in LDS; loop top waits vmcnt(4)
# baseline (speedup 1.0000x reference)
.LBB0_1009:
	s_cmp_lt_i32 s68, 9
	s_cselect_b64 s[6:7], -1, 0
	s_and_b64 s[6:7], s[6:7], s[4:5]
	s_andn2_b64 vcc, exec, s[6:7]
	s_cbranch_vccnz .LBB0_1013
	s_cmpk_gt_i32 s2, 0x3ff
	s_cbranch_scc1 .LBB0_1013
	v_lshrrev_b32_e32 v8, 3, v1
	v_and_b32_e32 v4, 7, v1
	s_movk_i32 s4, 0x84
	v_lshlrev_b32_e32 v6, 3, v4
	v_mov_b32_e32 v3, 0
	v_mad_u32_u24 v10, v8, s4, 0
	v_lshlrev_b32_e32 v2, 4, v4
	v_mul_u32_u24_e32 v4, 0x420, v4
	v_lshlrev_b32_e32 v5, 1, v8
	v_add3_u32 v9, 0, v4, v5
	v_lshl_add_u64 v[4:5], s[66:67], 0, v[2:3]
	s_mov_b64 s[8:9], 0x5c00000
	v_add_u32_e32 v10, v10, v2
	s_mov_b32 s5, 0
	v_lshl_add_u64 v[4:5], v[4:5], 0, s[8:9]
	s_lshl_b32 s10, s2, 8
	s_lshl_b32 s11, s70, 8
	v_lshlrev_b32_e32 v6, 1, v6
	v_mov_b32_e32 v7, v3
	v_add_u32_e32 v11, 0x2100, v10
	v_add_u32_e32 v12, 0x2108, v10
	v_add_u32_e32 v13, 0x4200, v10
	v_add_u32_e32 v14, 0x4208, v10
	v_add_u32_e32 v15, 0x6300, v10
	v_add_u32_e32 v16, 0x6308, v10
	s_mov_b32 s12, 0x20000
	s_mov_b32 s13, 0x40000
	s_mov_b32 s14, s2
	s_and_b32 s16, s14, 0xffffffc0
	v_add_u32_e32 v76, s16, v8
	v_ashrrev_i32_e32 v77, 31, v76
	s_and_b32 s17, s10, 0x3f00
	v_lshlrev_b64 v[76:77], 15, v[76:77]
	s_lshl_b32 s52, s17, 1
	s_mov_b32 s53, 0
	v_lshl_add_u64 v[76:77], s[64:65], 0, v[76:77]
	v_lshl_add_u64 v[76:77], v[76:77], 0, s[52:53]
	v_lshl_add_u64 v[76:77], v[76:77], 0, v[6:7]
	global_load_dwordx4 v[60:63], v[76:77], off
	global_load_dwordx4 v[64:67], v[76:77], off offset:128
	global_load_dwordx4 v[68:71], v[76:77], off offset:256
	global_load_dwordx4 v[72:75], v[76:77], off offset:384
	s_waitcnt vmcnt(0)
.LBB0_1012:
	s_and_b32 s8, s14, 0xffffffc0
	v_add_u32_e32 v18, s8, v8
	v_ashrrev_i32_e32 v19, 31, v18
	s_and_b32 s9, s10, 0x3f00
	v_lshlrev_b64 v[18:19], 15, v[18:19]
	s_lshl_b32 s4, s9, 1
	v_lshl_add_u64 v[18:19], s[64:65], 0, v[18:19]
	v_lshl_add_u64 v[18:19], v[18:19], 0, s[4:5]
	v_lshl_add_u64 v[34:35], v[18:19], 0, v[6:7]
	v_or_b32_e32 v2, s9, v8
	s_ashr_i32 s9, s8, 31
	v_lshl_add_u64 v[34:35], s[8:9], 1, v[4:5]
	v_lshlrev_b32_e32 v2, 11, v2
	v_lshl_add_u64 v[34:35], v[34:35], 0, v[2:3]
	v_add_co_u32_e32 v36, vcc, s12, v34
	s_add_i32 s14, s14, s70
	s_nop 0
	v_addc_co_u32_e32 v37, vcc, 0, v35, vcc
	v_add_co_u32_e32 v38, vcc, s13, v34
	s_add_i32 s10, s10, s11
	s_nop 0
	v_addc_co_u32_e32 v39, vcc, 0, v35, vcc
	s_cmpk_lt_i32 s14, 0x400
	v_add_co_u32_e32 v40, vcc, 0x60000, v34
	s_waitcnt vmcnt(4)
	ds_write2_b32 v10, v60, v61 offset1:1
	ds_write2_b32 v10, v62, v63 offset0:2 offset1:3
	ds_write2_b32 v11, v64, v65 offset1:1
	ds_write2_b32 v12, v66, v67 offset1:1
	ds_write2_b32 v13, v68, v69 offset1:1
	ds_write2_b32 v14, v70, v71 offset1:1
	ds_write2_b32 v15, v72, v73 offset1:1
	ds_write2_b32 v16, v74, v75 offset1:1
	s_waitcnt lgkmcnt(0)
	s_cmpk_ge_i32 s14, 0x400
	s_cbranch_scc1 .Lp8_nopf
	s_and_b32 s16, s14, 0xffffffc0
	v_add_u32_e32 v76, s16, v8
	v_ashrrev_i32_e32 v77, 31, v76
	s_and_b32 s17, s10, 0x3f00
	v_lshlrev_b64 v[76:77], 15, v[76:77]
	s_lshl_b32 s52, s17, 1
	s_mov_b32 s53, 0
	v_lshl_add_u64 v[76:77], s[64:65], 0, v[76:77]
	v_lshl_add_u64 v[76:77], v[76:77], 0, s[52:53]
	v_lshl_add_u64 v[76:77], v[76:77], 0, v[6:7]
	global_load_dwordx4 v[60:63], v[76:77], off
	global_load_dwordx4 v[64:67], v[76:77], off offset:128
	global_load_dwordx4 v[68:71], v[76:77], off offset:256
	global_load_dwordx4 v[72:75], v[76:77], off offset:384
.Lp8_nopf:
	s_barrier
	ds_read_u16 v2, v9
	ds_read_u16 v17, v9 offset:132
	ds_read_u16 v19, v9 offset:264
	ds_read_u16 v20, v9 offset:396
	ds_read_u16 v21, v9 offset:528
	ds_read_u16 v22, v9 offset:660
	ds_read_u16 v23, v9 offset:792
	ds_read_u16 v24, v9 offset:924
	ds_read_u16 v25, v9 offset:8448
	ds_read_u16 v26, v9 offset:8580
	ds_read_u16 v27, v9 offset:8712
	ds_read_u16 v28, v9 offset:8844
	ds_read_u16 v29, v9 offset:8976
	ds_read_u16 v30, v9 offset:9108
	ds_read_u16 v31, v9 offset:9240
	ds_read_u16 v32, v9 offset:9372
	ds_read_u16 v33, v9 offset:16896
	ds_read_u16 v42, v9 offset:17028
	ds_read_u16 v43, v9 offset:17160
	ds_read_u16 v44, v9 offset:17292
	ds_read_u16 v45, v9 offset:17424
	ds_read_u16 v46, v9 offset:17556
	ds_read_u16 v47, v9 offset:17688
	ds_read_u16 v48, v9 offset:17820
	ds_read_u16 v49, v9 offset:25344
	ds_read_u16 v50, v9 offset:25476
	ds_read_u16 v51, v9 offset:25608
	ds_read_u16 v52, v9 offset:25740
	ds_read_u16 v53, v9 offset:25872
	ds_read_u16 v54, v9 offset:26004
	ds_read_u16 v55, v9 offset:26136
	ds_read_u16 v56, v9 offset:26268
	s_waitcnt lgkmcnt(14)
	v_lshl_or_b32 v18, v17, 16, v2
	v_lshl_or_b32 v19, v20, 16, v19
	v_lshl_or_b32 v20, v22, 16, v21
	v_lshl_or_b32 v21, v24, 16, v23
	v_addc_co_u32_e32 v41, vcc, 0, v35, vcc
	v_lshl_or_b32 v22, v26, 16, v25
	v_lshl_or_b32 v23, v28, 16, v27
	v_lshl_or_b32 v24, v30, 16, v29
	v_lshl_or_b32 v25, v32, 16, v31
	v_lshl_or_b32 v26, v42, 16, v33
	s_waitcnt lgkmcnt(12)
	v_lshl_or_b32 v27, v44, 16, v43
	s_waitcnt lgkmcnt(10)
	v_lshl_or_b32 v28, v46, 16, v45
	s_waitcnt lgkmcnt(8)
	v_lshl_or_b32 v29, v48, 16, v47
	s_waitcnt lgkmcnt(6)
	v_lshl_or_b32 v30, v50, 16, v49
	s_waitcnt lgkmcnt(4)
	v_lshl_or_b32 v31, v52, 16, v51
	s_waitcnt lgkmcnt(2)
	v_lshl_or_b32 v32, v54, 16, v53
	s_waitcnt lgkmcnt(0)
	v_lshl_or_b32 v33, v56, 16, v55
	global_store_dwordx4 v[34:35], v[18:21], off
	global_store_dwordx4 v[36:37], v[22:25], off
	global_store_dwordx4 v[38:39], v[26:29], off
	global_store_dwordx4 v[40:41], v[30:33], off
	s_barrier
	s_cmpk_lt_i32 s14, 0x400
	s_cbranch_scc1 .LBB0_1012
